# P6b (conv boundary-row fix-up) hand-written: all loads of 3 iterations in flight together, 2 round trips instead of ~12 serialized ones
# speedup vs baseline: 1.0313x; 1.0006x over previous
; __device__ __forceinline__ unsigned cvt_pk_bf16(float lo, float hi) { unsigned r; asm volatile("v_cvt_pk_bf16_f32 %0, %1, %2" : "=v"(r) : "v"(lo), "v"(hi)); return r; }
; __global__ void __launch_bounds__(NTHR, 2) hybrid_block_fwd(Args a) {
;     ...
;         for (int idx = gtid; idx < 256 * 2 * (FF / 4); idx += NT) {
;             const int f4 = (idx % (FF / 4)) * 4, rr = (idx / (FF / 4)) & 1, blk = idx / (2 * (FF / 4));
;             const bool seq0 = (blk & 127) == 0; const size_t row = (size_t)blk * 64 + rr;
;             const f32x4 z = (f32x4){0.f, 0.f, 0.f, 0.f};
;             const f32x4 gc = *(const f32x4*)(HEADG + ((size_t)blk * 2 + rr) * FF + f4), vv = *(const f32x4*)(HEADV + ((size_t)blk * 2 + rr) * FF + f4);
;             f32x4 p1, p2;
;             if (rr == 0) { p1 = seq0 ? z : *(const f32x4*)(TAILG + ((size_t)(blk - 1) * 2 + 1) * FF + f4); p2 = seq0 ? z : *(const f32x4*)(TAILG + ((size_t)(blk - 1) * 2 + 0) * FF + f4); }
;             else { p1 = *(const f32x4*)(HEADG + ((size_t)blk * 2 + 0) * FF + f4); p2 = seq0 ? z : *(const f32x4*)(TAILG + ((size_t)(blk - 1) * 2 + 1) * FF + f4); }
;             const f32x4 cv = *(const f32x4*)(ffn_conv_b + f4) + *(const f32x4*)(ffn_conv_w + f4) * p2 + *(const f32x4*)(ffn_conv_w + FF + f4) * p1 + *(const f32x4*)(ffn_conv_w + 2 * FF + f4) * gc;
;             u32x2 w; w.x = cvt_pk_bf16(gelu_tanh(cv[0]) * vv[0], gelu_tanh(cv[1]) * vv[1]); w.y = cvt_pk_bf16(gelu_tanh(cv[2]) * vv[2], gelu_tanh(cv[3]) * vv[3]);
;             *(u32x2*)(ACT + row * FF + f4) = w;
.LBB0_1002:
	s_or_b64 exec, exec, s[0:1]
	s_waitcnt lgkmcnt(0)
	v_mov_b32_e32 v0, v212
	v_readlane_b32 s0, v248, 8
	s_barrier
	s_mov_b64 s[4:5], exec
	v_add_u32_e32 v1, s0, v0
	s_mov_b32 s6, 0x2aaaaaab
	v_mul_hi_i32 v2, v1, s6
	v_ashrrev_i32_e32 v3, 8, v2
	v_lshlrev_b32_e32 v4, 4, v1
	v_mul_u32_u24_e32 v5, 0x6000, v3
	v_sub_u32_e32 v4, v4, v5
	v_mov_b32_e32 v49, v3
	v_add_u32_e32 v6, v5, v4
	v_add_u32_e32 v7, 0x2700000, v6
	global_load_dwordx4 v[16:19], v7, s[94:95]
	v_add_u32_e32 v7, 0x3300000, v6
	global_load_dwordx4 v[20:23], v7, s[94:95]
	v_and_b32_e32 v8, 1, v3
	v_max_i32_e32 v9, 1, v3
	v_add_u32_e32 v9, -1, v9
	v_mul_u32_u24_e32 v9, 0x6000, v9
	v_add_u32_e32 v9, v9, v4
	v_cmp_eq_u32_e32 vcc, 1, v8
	v_mov_b32_e32 v7, 0x1b00000
	v_mov_b32_e32 v5, 0x2700000
	v_cndmask_b32_e32 v7, v7, v5, vcc
	v_add_u32_e32 v7, v7, v9
	global_load_dwordx4 v[24:27], v7, s[94:95]
	v_max_i32_e32 v9, 2, v3
	v_add_u32_e32 v9, -2, v9
	v_mul_u32_u24_e32 v9, 0x6000, v9
	v_add_u32_e32 v9, v9, v4
	v_add_u32_e32 v9, 0x1b00000, v9
	global_load_dwordx4 v[28:31], v9, s[94:95]
	global_load_dwordx4 v[32:35], v4, s[86:87]
	global_load_dwordx4 v[36:39], v4, s[84:85]
	global_load_dwordx4 v[40:43], v4, s[16:17]
	global_load_dwordx4 v[44:47], v4, s[18:19]
	v_lshrrev_b32_e32 v5, 1, v3
	v_lshl_or_b32 v5, v5, 6, v8
	v_mul_u32_u24_e32 v5, 0x3000, v5
	v_lshrrev_b32_e32 v7, 1, v4
	v_add_u32_e32 v5, v5, v7
	v_add_u32_e32 v48, 0x12700000, v5
	v_add_u32_e32 v1, 0x20000, v1
	v_mul_hi_i32 v2, v1, s6
	v_ashrrev_i32_e32 v3, 8, v2
	v_lshlrev_b32_e32 v4, 4, v1
	v_mul_u32_u24_e32 v5, 0x6000, v3
	v_sub_u32_e32 v4, v4, v5
	v_mov_b32_e32 v85, v3
	v_add_u32_e32 v6, v5, v4
	v_add_u32_e32 v7, 0x2700000, v6
	global_load_dwordx4 v[52:55], v7, s[94:95]
	v_add_u32_e32 v7, 0x3300000, v6
	global_load_dwordx4 v[56:59], v7, s[94:95]
	v_and_b32_e32 v8, 1, v3
	v_max_i32_e32 v9, 1, v3
	v_add_u32_e32 v9, -1, v9
	v_mul_u32_u24_e32 v9, 0x6000, v9
	v_add_u32_e32 v9, v9, v4
	v_cmp_eq_u32_e32 vcc, 1, v8
	v_mov_b32_e32 v7, 0x1b00000
	v_mov_b32_e32 v5, 0x2700000
	v_cndmask_b32_e32 v7, v7, v5, vcc
	v_add_u32_e32 v7, v7, v9
	global_load_dwordx4 v[60:63], v7, s[94:95]
	v_max_i32_e32 v9, 2, v3
	v_add_u32_e32 v9, -2, v9
	v_mul_u32_u24_e32 v9, 0x6000, v9
	v_add_u32_e32 v9, v9, v4
	v_add_u32_e32 v9, 0x1b00000, v9
	global_load_dwordx4 v[64:67], v9, s[94:95]
	global_load_dwordx4 v[68:71], v4, s[86:87]
	global_load_dwordx4 v[72:75], v4, s[84:85]
	global_load_dwordx4 v[76:79], v4, s[16:17]
	global_load_dwordx4 v[80:83], v4, s[18:19]
	v_lshrrev_b32_e32 v5, 1, v3
	v_lshl_or_b32 v5, v5, 6, v8
	v_mul_u32_u24_e32 v5, 0x3000, v5
	v_lshrrev_b32_e32 v7, 1, v4
	v_add_u32_e32 v5, v5, v7
	v_add_u32_e32 v84, 0x12700000, v5
	v_add_u32_e32 v1, 0x20000, v1
	v_mul_hi_i32 v2, v1, s6
	v_ashrrev_i32_e32 v3, 8, v2
	v_lshlrev_b32_e32 v4, 4, v1
	v_mul_u32_u24_e32 v5, 0x6000, v3
	v_sub_u32_e32 v4, v4, v5
	v_mov_b32_e32 v121, v3
	v_add_u32_e32 v6, v5, v4
	v_add_u32_e32 v7, 0x2700000, v6
	global_load_dwordx4 v[88:91], v7, s[94:95]
	v_add_u32_e32 v7, 0x3300000, v6
	global_load_dwordx4 v[92:95], v7, s[94:95]
	v_and_b32_e32 v8, 1, v3
	v_max_i32_e32 v9, 1, v3
	v_add_u32_e32 v9, -1, v9
	v_mul_u32_u24_e32 v9, 0x6000, v9
	v_add_u32_e32 v9, v9, v4
	v_cmp_eq_u32_e32 vcc, 1, v8
	v_mov_b32_e32 v7, 0x1b00000
	v_mov_b32_e32 v5, 0x2700000
	v_cndmask_b32_e32 v7, v7, v5, vcc
	v_add_u32_e32 v7, v7, v9
	global_load_dwordx4 v[96:99], v7, s[94:95]
	v_max_i32_e32 v9, 2, v3
	v_add_u32_e32 v9, -2, v9
	v_mul_u32_u24_e32 v9, 0x6000, v9
	v_add_u32_e32 v9, v9, v4
	v_add_u32_e32 v9, 0x1b00000, v9
	global_load_dwordx4 v[100:103], v9, s[94:95]
	global_load_dwordx4 v[104:107], v4, s[86:87]
	global_load_dwordx4 v[108:111], v4, s[84:85]
	global_load_dwordx4 v[112:115], v4, s[16:17]
	global_load_dwordx4 v[116:119], v4, s[18:19]
	v_lshrrev_b32_e32 v5, 1, v3
	v_lshl_or_b32 v5, v5, 6, v8
	v_mul_u32_u24_e32 v5, 0x3000, v5
	v_lshrrev_b32_e32 v7, 1, v4
	v_add_u32_e32 v5, v5, v7
	v_add_u32_e32 v120, 0x12700000, v5
	v_add_u32_e32 v1, 0x20000, v1
	s_waitcnt vmcnt(16)
	v_lshrrev_b32_e32 v2, 1, v49
	v_and_b32_e32 v2, 0x7f, v2
	v_cmp_eq_u32_e32 vcc, 0, v2
	v_and_b32_e32 v3, 1, v49
	v_cmp_eq_u32_e64 s[8:9], 0, v3
	s_nop 1
	s_and_b64 s[8:9], s[8:9], vcc
	s_nop 1
	v_cndmask_b32_e64 v28, v28, 0, vcc
	v_cndmask_b32_e64 v24, v24, 0, s[8:9]
	v_cndmask_b32_e64 v29, v29, 0, vcc
	v_cndmask_b32_e64 v25, v25, 0, s[8:9]
	v_cndmask_b32_e64 v30, v30, 0, vcc
	v_cndmask_b32_e64 v26, v26, 0, s[8:9]
	v_cndmask_b32_e64 v31, v31, 0, vcc
	v_cndmask_b32_e64 v27, v27, 0, s[8:9]
	v_pk_fma_f32 v[30:31], v[30:31], v[38:39], v[34:35]
	v_pk_fma_f32 v[28:29], v[28:29], v[36:37], v[32:33]
	v_pk_fma_f32 v[26:27], v[26:27], v[42:43], v[30:31]
	v_pk_fma_f32 v[24:25], v[24:25], v[40:41], v[28:29]
	v_pk_fma_f32 v[18:19], v[18:19], v[46:47], v[26:27]
	v_pk_fma_f32 v[16:17], v[16:17], v[44:45], v[24:25]
	v_mul_f32_e32 v32, 0x3d922279, v16
	v_mul_f32_e32 v33, 0x3d922279, v17
	v_mul_f32_e32 v34, 0x3d922279, v18
	v_mul_f32_e32 v35, 0x3d922279, v19
	v_fmaak_f32 v32, v16, v32, 0x3fcc422a
	v_fmaak_f32 v33, v17, v33, 0x3fcc422a
	v_fmaak_f32 v34, v18, v34, 0x3fcc422a
	v_fmaak_f32 v35, v19, v35, 0x3fcc422a
	v_mul_f32_e32 v32, v16, v32
	v_mul_f32_e32 v33, v17, v33
	v_mul_f32_e32 v34, v18, v34
	v_mul_f32_e32 v35, v19, v35
	v_mul_f32_e32 v32, 0xbfb8aa3b, v32
	v_mul_f32_e32 v33, 0xbfb8aa3b, v33
	v_mul_f32_e32 v34, 0xbfb8aa3b, v34
	v_mul_f32_e32 v35, 0xbfb8aa3b, v35
	v_exp_f32_e32 v32, v32
	v_exp_f32_e32 v33, v33
	v_exp_f32_e32 v34, v34
	v_exp_f32_e32 v35, v35
	v_add_f32_e32 v32, 1.0, v32
	v_add_f32_e32 v33, 1.0, v33
	v_add_f32_e32 v34, 1.0, v34
	v_add_f32_e32 v35, 1.0, v35
	v_rcp_f32_e32 v32, v32
	v_rcp_f32_e32 v33, v33
	v_rcp_f32_e32 v34, v34
	v_rcp_f32_e32 v35, v35
	v_mul_f32_e32 v16, v16, v32
	v_mul_f32_e32 v17, v17, v33
	v_mul_f32_e32 v18, v18, v34
	v_mul_f32_e32 v19, v19, v35
	v_mul_f32_e32 v16, v20, v16
	v_mul_f32_e32 v17, v21, v17
	v_mul_f32_e32 v18, v22, v18
	v_mul_f32_e32 v19, v23, v19
	v_cvt_pk_bf16_f32 v16, v16, v17
	v_cvt_pk_bf16_f32 v17, v18, v19
	global_store_dwordx2 v48, v[16:17], s[94:95]
	s_waitcnt vmcnt(9)
; __device__ __forceinline__ unsigned cvt_pk_bf16(float lo, float hi) { unsigned r; asm volatile("v_cvt_pk_bf16_f32 %0, %1, %2" : "=v"(r) : "v"(lo), "v"(hi)); return r; }
; __global__ void __launch_bounds__(NTHR, 2) hybrid_block_fwd(Args a) {
;     ...
;         for (int idx = gtid; idx < 256 * 2 * (FF / 4); idx += NT) {
;             const int f4 = (idx % (FF / 4)) * 4, rr = (idx / (FF / 4)) & 1, blk = idx / (2 * (FF / 4));
;             const bool seq0 = (blk & 127) == 0; const size_t row = (size_t)blk * 64 + rr;
;             const f32x4 z = (f32x4){0.f, 0.f, 0.f, 0.f};
;             const f32x4 gc = *(const f32x4*)(HEADG + ((size_t)blk * 2 + rr) * FF + f4), vv = *(const f32x4*)(HEADV + ((size_t)blk * 2 + rr) * FF + f4);
;             f32x4 p1, p2;
;             if (rr == 0) { p1 = seq0 ? z : *(const f32x4*)(TAILG + ((size_t)(blk - 1) * 2 + 1) * FF + f4); p2 = seq0 ? z : *(const f32x4*)(TAILG + ((size_t)(blk - 1) * 2 + 0) * FF + f4); }
;             else { p1 = *(const f32x4*)(HEADG + ((size_t)blk * 2 + 0) * FF + f4); p2 = seq0 ? z : *(const f32x4*)(TAILG + ((size_t)(blk - 1) * 2 + 1) * FF + f4); }
;             const f32x4 cv = *(const f32x4*)(ffn_conv_b + f4) + *(const f32x4*)(ffn_conv_w + f4) * p2 + *(const f32x4*)(ffn_conv_w + FF + f4) * p1 + *(const f32x4*)(ffn_conv_w + 2 * FF + f4) * gc;
;             u32x2 w; w.x = cvt_pk_bf16(gelu_tanh(cv[0]) * vv[0], gelu_tanh(cv[1]) * vv[1]); w.y = cvt_pk_bf16(gelu_tanh(cv[2]) * vv[2], gelu_tanh(cv[3]) * vv[3]);
;             *(u32x2*)(ACT + row * FF + f4) = w;
	v_lshrrev_b32_e32 v2, 1, v85
	v_and_b32_e32 v2, 0x7f, v2
	v_cmp_eq_u32_e32 vcc, 0, v2
	v_and_b32_e32 v3, 1, v85
	v_cmp_eq_u32_e64 s[8:9], 0, v3
	s_nop 1
	s_and_b64 s[8:9], s[8:9], vcc
	s_nop 1
	v_cndmask_b32_e64 v64, v64, 0, vcc
	v_cndmask_b32_e64 v60, v60, 0, s[8:9]
	v_cndmask_b32_e64 v65, v65, 0, vcc
	v_cndmask_b32_e64 v61, v61, 0, s[8:9]
	v_cndmask_b32_e64 v66, v66, 0, vcc
	v_cndmask_b32_e64 v62, v62, 0, s[8:9]
	v_cndmask_b32_e64 v67, v67, 0, vcc
	v_cndmask_b32_e64 v63, v63, 0, s[8:9]
	v_pk_fma_f32 v[66:67], v[66:67], v[74:75], v[70:71]
	v_pk_fma_f32 v[64:65], v[64:65], v[72:73], v[68:69]
	v_pk_fma_f32 v[62:63], v[62:63], v[78:79], v[66:67]
	v_pk_fma_f32 v[60:61], v[60:61], v[76:77], v[64:65]
	v_pk_fma_f32 v[54:55], v[54:55], v[82:83], v[62:63]
	v_pk_fma_f32 v[52:53], v[52:53], v[80:81], v[60:61]
	v_mul_f32_e32 v68, 0x3d922279, v52
	v_mul_f32_e32 v69, 0x3d922279, v53
	v_mul_f32_e32 v70, 0x3d922279, v54
	v_mul_f32_e32 v71, 0x3d922279, v55
	v_fmaak_f32 v68, v52, v68, 0x3fcc422a
	v_fmaak_f32 v69, v53, v69, 0x3fcc422a
	v_fmaak_f32 v70, v54, v70, 0x3fcc422a
	v_fmaak_f32 v71, v55, v71, 0x3fcc422a
	v_mul_f32_e32 v68, v52, v68
	v_mul_f32_e32 v69, v53, v69
	v_mul_f32_e32 v70, v54, v70
	v_mul_f32_e32 v71, v55, v71
	v_mul_f32_e32 v68, 0xbfb8aa3b, v68
	v_mul_f32_e32 v69, 0xbfb8aa3b, v69
	v_mul_f32_e32 v70, 0xbfb8aa3b, v70
	v_mul_f32_e32 v71, 0xbfb8aa3b, v71
	v_exp_f32_e32 v68, v68
	v_exp_f32_e32 v69, v69
	v_exp_f32_e32 v70, v70
	v_exp_f32_e32 v71, v71
	v_add_f32_e32 v68, 1.0, v68
	v_add_f32_e32 v69, 1.0, v69
	v_add_f32_e32 v70, 1.0, v70
	v_add_f32_e32 v71, 1.0, v71
	v_rcp_f32_e32 v68, v68
	v_rcp_f32_e32 v69, v69
	v_rcp_f32_e32 v70, v70
	v_rcp_f32_e32 v71, v71
	v_mul_f32_e32 v52, v52, v68
	v_mul_f32_e32 v53, v53, v69
	v_mul_f32_e32 v54, v54, v70
	v_mul_f32_e32 v55, v55, v71
	v_mul_f32_e32 v52, v56, v52
	v_mul_f32_e32 v53, v57, v53
	v_mul_f32_e32 v54, v58, v54
	v_mul_f32_e32 v55, v59, v55
	v_cvt_pk_bf16_f32 v52, v52, v53
	v_cvt_pk_bf16_f32 v53, v54, v55
	global_store_dwordx2 v84, v[52:53], s[94:95]
	s_waitcnt vmcnt(2)
	v_lshrrev_b32_e32 v2, 1, v121
	v_and_b32_e32 v2, 0x7f, v2
	v_cmp_eq_u32_e32 vcc, 0, v2
	v_and_b32_e32 v3, 1, v121
	v_cmp_eq_u32_e64 s[8:9], 0, v3
	s_nop 1
	s_and_b64 s[8:9], s[8:9], vcc
	s_nop 1
	v_cndmask_b32_e64 v100, v100, 0, vcc
	v_cndmask_b32_e64 v96, v96, 0, s[8:9]
	v_cndmask_b32_e64 v101, v101, 0, vcc
	v_cndmask_b32_e64 v97, v97, 0, s[8:9]
	v_cndmask_b32_e64 v102, v102, 0, vcc
	v_cndmask_b32_e64 v98, v98, 0, s[8:9]
	v_cndmask_b32_e64 v103, v103, 0, vcc
	v_cndmask_b32_e64 v99, v99, 0, s[8:9]
	v_pk_fma_f32 v[102:103], v[102:103], v[110:111], v[106:107]
	v_pk_fma_f32 v[100:101], v[100:101], v[108:109], v[104:105]
	v_pk_fma_f32 v[98:99], v[98:99], v[114:115], v[102:103]
	v_pk_fma_f32 v[96:97], v[96:97], v[112:113], v[100:101]
	v_pk_fma_f32 v[90:91], v[90:91], v[118:119], v[98:99]
	v_pk_fma_f32 v[88:89], v[88:89], v[116:117], v[96:97]
	v_mul_f32_e32 v104, 0x3d922279, v88
	v_mul_f32_e32 v105, 0x3d922279, v89
	v_mul_f32_e32 v106, 0x3d922279, v90
	v_mul_f32_e32 v107, 0x3d922279, v91
	v_fmaak_f32 v104, v88, v104, 0x3fcc422a
	v_fmaak_f32 v105, v89, v105, 0x3fcc422a
	v_fmaak_f32 v106, v90, v106, 0x3fcc422a
	v_fmaak_f32 v107, v91, v107, 0x3fcc422a
	v_mul_f32_e32 v104, v88, v104
	v_mul_f32_e32 v105, v89, v105
	v_mul_f32_e32 v106, v90, v106
	v_mul_f32_e32 v107, v91, v107
	v_mul_f32_e32 v104, 0xbfb8aa3b, v104
	v_mul_f32_e32 v105, 0xbfb8aa3b, v105
	v_mul_f32_e32 v106, 0xbfb8aa3b, v106
	v_mul_f32_e32 v107, 0xbfb8aa3b, v107
	v_exp_f32_e32 v104, v104
	v_exp_f32_e32 v105, v105
	v_exp_f32_e32 v106, v106
	v_exp_f32_e32 v107, v107
	v_add_f32_e32 v104, 1.0, v104
	v_add_f32_e32 v105, 1.0, v105
	v_add_f32_e32 v106, 1.0, v106
	v_add_f32_e32 v107, 1.0, v107
	v_rcp_f32_e32 v104, v104
	v_rcp_f32_e32 v105, v105
	v_rcp_f32_e32 v106, v106
	v_rcp_f32_e32 v107, v107
	v_mul_f32_e32 v88, v88, v104
	v_mul_f32_e32 v89, v89, v105
	v_mul_f32_e32 v90, v90, v106
	v_mul_f32_e32 v91, v91, v107
	v_mul_f32_e32 v88, v92, v88
	v_mul_f32_e32 v89, v93, v89
	v_mul_f32_e32 v90, v94, v90
	v_mul_f32_e32 v91, v95, v91
	v_cvt_pk_bf16_f32 v88, v88, v89
	v_cvt_pk_bf16_f32 v89, v90, v91
	global_store_dwordx2 v120, v[88:89], s[94:95]
	v_mul_hi_i32 v2, v1, s6
	v_ashrrev_i32_e32 v3, 8, v2
	v_lshlrev_b32_e32 v4, 4, v1
	v_mul_u32_u24_e32 v5, 0x6000, v3
	v_sub_u32_e32 v4, v4, v5
	v_mov_b32_e32 v49, v3
	v_add_u32_e32 v6, v5, v4
	v_add_u32_e32 v7, 0x2700000, v6
	global_load_dwordx4 v[16:19], v7, s[94:95]
	v_add_u32_e32 v7, 0x3300000, v6
	global_load_dwordx4 v[20:23], v7, s[94:95]
	v_and_b32_e32 v8, 1, v3
	v_max_i32_e32 v9, 1, v3
	v_add_u32_e32 v9, -1, v9
	v_mul_u32_u24_e32 v9, 0x6000, v9
	v_add_u32_e32 v9, v9, v4
	v_cmp_eq_u32_e32 vcc, 1, v8
	v_mov_b32_e32 v7, 0x1b00000
	v_mov_b32_e32 v5, 0x2700000
	v_cndmask_b32_e32 v7, v7, v5, vcc
	v_add_u32_e32 v7, v7, v9
	global_load_dwordx4 v[24:27], v7, s[94:95]
	v_max_i32_e32 v9, 2, v3
	v_add_u32_e32 v9, -2, v9
	v_mul_u32_u24_e32 v9, 0x6000, v9
	v_add_u32_e32 v9, v9, v4
	v_add_u32_e32 v9, 0x1b00000, v9
	global_load_dwordx4 v[28:31], v9, s[94:95]
	global_load_dwordx4 v[32:35], v4, s[86:87]
	global_load_dwordx4 v[36:39], v4, s[84:85]
	global_load_dwordx4 v[40:43], v4, s[16:17]
	global_load_dwordx4 v[44:47], v4, s[18:19]
	v_lshrrev_b32_e32 v5, 1, v3
	v_lshl_or_b32 v5, v5, 6, v8
	v_mul_u32_u24_e32 v5, 0x3000, v5
	v_lshrrev_b32_e32 v7, 1, v4
	v_add_u32_e32 v5, v5, v7
	v_add_u32_e32 v48, 0x12700000, v5
	v_add_u32_e32 v1, 0x20000, v1
	v_mul_hi_i32 v2, v1, s6
	v_ashrrev_i32_e32 v3, 8, v2
	v_lshlrev_b32_e32 v4, 4, v1
	v_mul_u32_u24_e32 v5, 0x6000, v3
	v_sub_u32_e32 v4, v4, v5
	v_mov_b32_e32 v85, v3
	v_add_u32_e32 v6, v5, v4
	v_add_u32_e32 v7, 0x2700000, v6
; __device__ __forceinline__ unsigned cvt_pk_bf16(float lo, float hi) { unsigned r; asm volatile("v_cvt_pk_bf16_f32 %0, %1, %2" : "=v"(r) : "v"(lo), "v"(hi)); return r; }
; __global__ void __launch_bounds__(NTHR, 2) hybrid_block_fwd(Args a) {
;     ...
;         for (int idx = gtid; idx < 256 * 2 * (FF / 4); idx += NT) {
;             const int f4 = (idx % (FF / 4)) * 4, rr = (idx / (FF / 4)) & 1, blk = idx / (2 * (FF / 4));
;             const bool seq0 = (blk & 127) == 0; const size_t row = (size_t)blk * 64 + rr;
;             const f32x4 z = (f32x4){0.f, 0.f, 0.f, 0.f};
;             const f32x4 gc = *(const f32x4*)(HEADG + ((size_t)blk * 2 + rr) * FF + f4), vv = *(const f32x4*)(HEADV + ((size_t)blk * 2 + rr) * FF + f4);
;             f32x4 p1, p2;
;             if (rr == 0) { p1 = seq0 ? z : *(const f32x4*)(TAILG + ((size_t)(blk - 1) * 2 + 1) * FF + f4); p2 = seq0 ? z : *(const f32x4*)(TAILG + ((size_t)(blk - 1) * 2 + 0) * FF + f4); }
;             else { p1 = *(const f32x4*)(HEADG + ((size_t)blk * 2 + 0) * FF + f4); p2 = seq0 ? z : *(const f32x4*)(TAILG + ((size_t)(blk - 1) * 2 + 1) * FF + f4); }
;             const f32x4 cv = *(const f32x4*)(ffn_conv_b + f4) + *(const f32x4*)(ffn_conv_w + f4) * p2 + *(const f32x4*)(ffn_conv_w + FF + f4) * p1 + *(const f32x4*)(ffn_conv_w + 2 * FF + f4) * gc;
;             u32x2 w; w.x = cvt_pk_bf16(gelu_tanh(cv[0]) * vv[0], gelu_tanh(cv[1]) * vv[1]); w.y = cvt_pk_bf16(gelu_tanh(cv[2]) * vv[2], gelu_tanh(cv[3]) * vv[3]);
;             *(u32x2*)(ACT + row * FF + f4) = w;
	global_load_dwordx4 v[52:55], v7, s[94:95]
	v_add_u32_e32 v7, 0x3300000, v6
	global_load_dwordx4 v[56:59], v7, s[94:95]
	v_and_b32_e32 v8, 1, v3
	v_max_i32_e32 v9, 1, v3
	v_add_u32_e32 v9, -1, v9
	v_mul_u32_u24_e32 v9, 0x6000, v9
	v_add_u32_e32 v9, v9, v4
	v_cmp_eq_u32_e32 vcc, 1, v8
	v_mov_b32_e32 v7, 0x1b00000
	v_mov_b32_e32 v5, 0x2700000
	v_cndmask_b32_e32 v7, v7, v5, vcc
	v_add_u32_e32 v7, v7, v9
	global_load_dwordx4 v[60:63], v7, s[94:95]
	v_max_i32_e32 v9, 2, v3
	v_add_u32_e32 v9, -2, v9
	v_mul_u32_u24_e32 v9, 0x6000, v9
	v_add_u32_e32 v9, v9, v4
	v_add_u32_e32 v9, 0x1b00000, v9
	global_load_dwordx4 v[64:67], v9, s[94:95]
	global_load_dwordx4 v[68:71], v4, s[86:87]
	global_load_dwordx4 v[72:75], v4, s[84:85]
	global_load_dwordx4 v[76:79], v4, s[16:17]
	global_load_dwordx4 v[80:83], v4, s[18:19]
	v_lshrrev_b32_e32 v5, 1, v3
	v_lshl_or_b32 v5, v5, 6, v8
	v_mul_u32_u24_e32 v5, 0x3000, v5
	v_lshrrev_b32_e32 v7, 1, v4
	v_add_u32_e32 v5, v5, v7
	v_add_u32_e32 v84, 0x12700000, v5
	v_add_u32_e32 v1, 0x20000, v1
	v_mul_hi_i32 v2, v1, s6
	v_ashrrev_i32_e32 v3, 8, v2
	v_lshlrev_b32_e32 v4, 4, v1
	v_mul_u32_u24_e32 v5, 0x6000, v3
	v_sub_u32_e32 v4, v4, v5
	v_mov_b32_e32 v121, v3
	v_add_u32_e32 v6, v5, v4
	v_add_u32_e32 v7, 0x2700000, v6
	global_load_dwordx4 v[88:91], v7, s[94:95]
	v_add_u32_e32 v7, 0x3300000, v6
	global_load_dwordx4 v[92:95], v7, s[94:95]
	v_and_b32_e32 v8, 1, v3
	v_max_i32_e32 v9, 1, v3
	v_add_u32_e32 v9, -1, v9
	v_mul_u32_u24_e32 v9, 0x6000, v9
	v_add_u32_e32 v9, v9, v4
	v_cmp_eq_u32_e32 vcc, 1, v8
	v_mov_b32_e32 v7, 0x1b00000
	v_mov_b32_e32 v5, 0x2700000
	v_cndmask_b32_e32 v7, v7, v5, vcc
	v_add_u32_e32 v7, v7, v9
	global_load_dwordx4 v[96:99], v7, s[94:95]
	v_max_i32_e32 v9, 2, v3
	v_add_u32_e32 v9, -2, v9
	v_mul_u32_u24_e32 v9, 0x6000, v9
	v_add_u32_e32 v9, v9, v4
	v_add_u32_e32 v9, 0x1b00000, v9
	global_load_dwordx4 v[100:103], v9, s[94:95]
	global_load_dwordx4 v[104:107], v4, s[86:87]
	global_load_dwordx4 v[108:111], v4, s[84:85]
	global_load_dwordx4 v[112:115], v4, s[16:17]
	global_load_dwordx4 v[116:119], v4, s[18:19]
	v_lshrrev_b32_e32 v5, 1, v3
	v_lshl_or_b32 v5, v5, 6, v8
	v_mul_u32_u24_e32 v5, 0x3000, v5
	v_lshrrev_b32_e32 v7, 1, v4
	v_add_u32_e32 v5, v5, v7
	v_add_u32_e32 v120, 0x12700000, v5
	v_add_u32_e32 v1, 0x20000, v1
	s_waitcnt vmcnt(16)
	v_lshrrev_b32_e32 v2, 1, v49
	v_and_b32_e32 v2, 0x7f, v2
	v_cmp_eq_u32_e32 vcc, 0, v2
	v_and_b32_e32 v3, 1, v49
	v_cmp_eq_u32_e64 s[8:9], 0, v3
	s_nop 1
	s_and_b64 s[8:9], s[8:9], vcc
	s_nop 1
	v_cndmask_b32_e64 v28, v28, 0, vcc
	v_cndmask_b32_e64 v24, v24, 0, s[8:9]
	v_cndmask_b32_e64 v29, v29, 0, vcc
	v_cndmask_b32_e64 v25, v25, 0, s[8:9]
	v_cndmask_b32_e64 v30, v30, 0, vcc
	v_cndmask_b32_e64 v26, v26, 0, s[8:9]
	v_cndmask_b32_e64 v31, v31, 0, vcc
	v_cndmask_b32_e64 v27, v27, 0, s[8:9]
	v_pk_fma_f32 v[30:31], v[30:31], v[38:39], v[34:35]
	v_pk_fma_f32 v[28:29], v[28:29], v[36:37], v[32:33]
	v_pk_fma_f32 v[26:27], v[26:27], v[42:43], v[30:31]
	v_pk_fma_f32 v[24:25], v[24:25], v[40:41], v[28:29]
	v_pk_fma_f32 v[18:19], v[18:19], v[46:47], v[26:27]
	v_pk_fma_f32 v[16:17], v[16:17], v[44:45], v[24:25]
	v_mul_f32_e32 v32, 0x3d922279, v16
	v_mul_f32_e32 v33, 0x3d922279, v17
	v_mul_f32_e32 v34, 0x3d922279, v18
	v_mul_f32_e32 v35, 0x3d922279, v19
	v_fmaak_f32 v32, v16, v32, 0x3fcc422a
	v_fmaak_f32 v33, v17, v33, 0x3fcc422a
	v_fmaak_f32 v34, v18, v34, 0x3fcc422a
	v_fmaak_f32 v35, v19, v35, 0x3fcc422a
	v_mul_f32_e32 v32, v16, v32
	v_mul_f32_e32 v33, v17, v33
	v_mul_f32_e32 v34, v18, v34
	v_mul_f32_e32 v35, v19, v35
	v_mul_f32_e32 v32, 0xbfb8aa3b, v32
	v_mul_f32_e32 v33, 0xbfb8aa3b, v33
	v_mul_f32_e32 v34, 0xbfb8aa3b, v34
	v_mul_f32_e32 v35, 0xbfb8aa3b, v35
	v_exp_f32_e32 v32, v32
	v_exp_f32_e32 v33, v33
	v_exp_f32_e32 v34, v34
	v_exp_f32_e32 v35, v35
	v_add_f32_e32 v32, 1.0, v32
	v_add_f32_e32 v33, 1.0, v33
	v_add_f32_e32 v34, 1.0, v34
	v_add_f32_e32 v35, 1.0, v35
	v_rcp_f32_e32 v32, v32
	v_rcp_f32_e32 v33, v33
	v_rcp_f32_e32 v34, v34
	v_rcp_f32_e32 v35, v35
	v_mul_f32_e32 v16, v16, v32
	v_mul_f32_e32 v17, v17, v33
	v_mul_f32_e32 v18, v18, v34
	v_mul_f32_e32 v19, v19, v35
	v_mul_f32_e32 v16, v20, v16
	v_mul_f32_e32 v17, v21, v17
	v_mul_f32_e32 v18, v22, v18
	v_mul_f32_e32 v19, v23, v19
	v_cvt_pk_bf16_f32 v16, v16, v17
	v_cvt_pk_bf16_f32 v17, v18, v19
	global_store_dwordx2 v48, v[16:17], s[94:95]
	s_waitcnt vmcnt(9)
; __device__ __forceinline__ void xcd_barrier_complete(unsigned* bar, unsigned x, unsigned& nloc, unsigned& nx) {
;     const unsigned G = gridDim.x * gridDim.y * gridDim.z;
;     unsigned sum, cnt, mine, sp = 0u;
;     for (;;) {
;         sum = 0u; cnt = 0u; mine = 0u;
; #pragma unroll
;         for (unsigned j = 0; j < 16; ++j) { const unsigned c = xb_ld(&bar[XB_XCNT(j)]); sum += c; cnt += (c > 0u) ? 1u : 0u; mine = (j == x) ? c : mine; }
;         if (sum == G) break;
;         __builtin_amdgcn_s_sleep(1);
;         if ((++sp & 255u) == 0u) { if (xb_ld(&bar[XB_TMO])) break; if (sp > XB_SPIN_CAP) { atomicAdd(&bar[XB_TMO], 1u); break; } }
;     }
;     nloc = mine > 0u ? mine : 1u; nx = cnt > 0u ? cnt : 1u;
; }
; __device__ __forceinline__ void xcd_barrier(const XcdBarrier& b) {
;     asm volatile("s_waitcnt vmcnt(0)" ::: "memory");
;     __syncthreads();
;     if (threadIdx.x == 0) {
;         unsigned* bar = b.bar;
;         __builtin_amdgcn_s_waitcnt(0);
;         unsigned nloc = b.st[0], nx = b.st[1];
; __global__ void __launch_bounds__(NTHR, 2) hybrid_block_fwd(Args a) {
;     ...
;         for (int idx = gtid; idx < 256 * 2 * (FF / 4); idx += NT) {
;             const int f4 = (idx % (FF / 4)) * 4, rr = (idx / (FF / 4)) & 1, blk = idx / (2 * (FF / 4));
;             const bool seq0 = (blk & 127) == 0; const size_t row = (size_t)blk * 64 + rr;
;             const f32x4 z = (f32x4){0.f, 0.f, 0.f, 0.f};
;             const f32x4 gc = *(const f32x4*)(HEADG + ((size_t)blk * 2 + rr) * FF + f4), vv = *(const f32x4*)(HEADV + ((size_t)blk * 2 + rr) * FF + f4);
;             f32x4 p1, p2;
;             if (rr == 0) { p1 = seq0 ? z : *(const f32x4*)(TAILG + ((size_t)(blk - 1) * 2 + 1) * FF + f4); p2 = seq0 ? z : *(const f32x4*)(TAILG + ((size_t)(blk - 1) * 2 + 0) * FF + f4); }
;             else { p1 = *(const f32x4*)(HEADG + ((size_t)blk * 2 + 0) * FF + f4); p2 = seq0 ? z : *(const f32x4*)(TAILG + ((size_t)(blk - 1) * 2 + 1) * FF + f4); }
;             const f32x4 cv = *(const f32x4*)(ffn_conv_b + f4) + *(const f32x4*)(ffn_conv_w + f4) * p2 + *(const f32x4*)(ffn_conv_w + FF + f4) * p1 + *(const f32x4*)(ffn_conv_w + 2 * FF + f4) * gc;
;             u32x2 w; w.x = cvt_pk_bf16(gelu_tanh(cv[0]) * vv[0], gelu_tanh(cv[1]) * vv[1]); w.y = cvt_pk_bf16(gelu_tanh(cv[2]) * vv[2], gelu_tanh(cv[3]) * vv[3]);
;             *(u32x2*)(ACT + row * FF + f4) = w;
	v_lshrrev_b32_e32 v2, 1, v85
	v_and_b32_e32 v2, 0x7f, v2
	v_cmp_eq_u32_e32 vcc, 0, v2
	v_and_b32_e32 v3, 1, v85
	v_cmp_eq_u32_e64 s[8:9], 0, v3
	s_nop 1
	s_and_b64 s[8:9], s[8:9], vcc
	s_nop 1
	v_cndmask_b32_e64 v64, v64, 0, vcc
	v_cndmask_b32_e64 v60, v60, 0, s[8:9]
	v_cndmask_b32_e64 v65, v65, 0, vcc
	v_cndmask_b32_e64 v61, v61, 0, s[8:9]
	v_cndmask_b32_e64 v66, v66, 0, vcc
	v_cndmask_b32_e64 v62, v62, 0, s[8:9]
	v_cndmask_b32_e64 v67, v67, 0, vcc
	v_cndmask_b32_e64 v63, v63, 0, s[8:9]
	v_pk_fma_f32 v[66:67], v[66:67], v[74:75], v[70:71]
	v_pk_fma_f32 v[64:65], v[64:65], v[72:73], v[68:69]
	v_pk_fma_f32 v[62:63], v[62:63], v[78:79], v[66:67]
	v_pk_fma_f32 v[60:61], v[60:61], v[76:77], v[64:65]
	v_pk_fma_f32 v[54:55], v[54:55], v[82:83], v[62:63]
	v_pk_fma_f32 v[52:53], v[52:53], v[80:81], v[60:61]
	v_mul_f32_e32 v68, 0x3d922279, v52
	v_mul_f32_e32 v69, 0x3d922279, v53
	v_mul_f32_e32 v70, 0x3d922279, v54
	v_mul_f32_e32 v71, 0x3d922279, v55
	v_fmaak_f32 v68, v52, v68, 0x3fcc422a
	v_fmaak_f32 v69, v53, v69, 0x3fcc422a
	v_fmaak_f32 v70, v54, v70, 0x3fcc422a
	v_fmaak_f32 v71, v55, v71, 0x3fcc422a
	v_mul_f32_e32 v68, v52, v68
	v_mul_f32_e32 v69, v53, v69
	v_mul_f32_e32 v70, v54, v70
	v_mul_f32_e32 v71, v55, v71
	v_mul_f32_e32 v68, 0xbfb8aa3b, v68
	v_mul_f32_e32 v69, 0xbfb8aa3b, v69
	v_mul_f32_e32 v70, 0xbfb8aa3b, v70
	v_mul_f32_e32 v71, 0xbfb8aa3b, v71
	v_exp_f32_e32 v68, v68
	v_exp_f32_e32 v69, v69
	v_exp_f32_e32 v70, v70
	v_exp_f32_e32 v71, v71
	v_add_f32_e32 v68, 1.0, v68
	v_add_f32_e32 v69, 1.0, v69
	v_add_f32_e32 v70, 1.0, v70
	v_add_f32_e32 v71, 1.0, v71
	v_rcp_f32_e32 v68, v68
	v_rcp_f32_e32 v69, v69
	v_rcp_f32_e32 v70, v70
	v_rcp_f32_e32 v71, v71
	v_mul_f32_e32 v52, v52, v68
	v_mul_f32_e32 v53, v53, v69
	v_mul_f32_e32 v54, v54, v70
	v_mul_f32_e32 v55, v55, v71
	v_mul_f32_e32 v52, v56, v52
	v_mul_f32_e32 v53, v57, v53
	v_mul_f32_e32 v54, v58, v54
	v_mul_f32_e32 v55, v59, v55
	v_cvt_pk_bf16_f32 v52, v52, v53
	v_cvt_pk_bf16_f32 v53, v54, v55
	global_store_dwordx2 v84, v[52:53], s[94:95]
	s_waitcnt vmcnt(2)
	v_lshrrev_b32_e32 v2, 1, v121
	v_and_b32_e32 v2, 0x7f, v2
	v_cmp_eq_u32_e32 vcc, 0, v2
	v_and_b32_e32 v3, 1, v121
	v_cmp_eq_u32_e64 s[8:9], 0, v3
	s_nop 1
	s_and_b64 s[8:9], s[8:9], vcc
	s_nop 1
	v_cndmask_b32_e64 v100, v100, 0, vcc
	v_cndmask_b32_e64 v96, v96, 0, s[8:9]
	v_cndmask_b32_e64 v101, v101, 0, vcc
	v_cndmask_b32_e64 v97, v97, 0, s[8:9]
	v_cndmask_b32_e64 v102, v102, 0, vcc
	v_cndmask_b32_e64 v98, v98, 0, s[8:9]
	v_cndmask_b32_e64 v103, v103, 0, vcc
	v_cndmask_b32_e64 v99, v99, 0, s[8:9]
	v_pk_fma_f32 v[102:103], v[102:103], v[110:111], v[106:107]
	v_pk_fma_f32 v[100:101], v[100:101], v[108:109], v[104:105]
	v_pk_fma_f32 v[98:99], v[98:99], v[114:115], v[102:103]
	v_pk_fma_f32 v[96:97], v[96:97], v[112:113], v[100:101]
	v_pk_fma_f32 v[90:91], v[90:91], v[118:119], v[98:99]
	v_pk_fma_f32 v[88:89], v[88:89], v[116:117], v[96:97]
	v_mul_f32_e32 v104, 0x3d922279, v88
	v_mul_f32_e32 v105, 0x3d922279, v89
	v_mul_f32_e32 v106, 0x3d922279, v90
	v_mul_f32_e32 v107, 0x3d922279, v91
	v_fmaak_f32 v104, v88, v104, 0x3fcc422a
	v_fmaak_f32 v105, v89, v105, 0x3fcc422a
	v_fmaak_f32 v106, v90, v106, 0x3fcc422a
	v_fmaak_f32 v107, v91, v107, 0x3fcc422a
	v_mul_f32_e32 v104, v88, v104
	v_mul_f32_e32 v105, v89, v105
	v_mul_f32_e32 v106, v90, v106
	v_mul_f32_e32 v107, v91, v107
	v_mul_f32_e32 v104, 0xbfb8aa3b, v104
	v_mul_f32_e32 v105, 0xbfb8aa3b, v105
	v_mul_f32_e32 v106, 0xbfb8aa3b, v106
	v_mul_f32_e32 v107, 0xbfb8aa3b, v107
	v_exp_f32_e32 v104, v104
	v_exp_f32_e32 v105, v105
	v_exp_f32_e32 v106, v106
	v_exp_f32_e32 v107, v107
	v_add_f32_e32 v104, 1.0, v104
	v_add_f32_e32 v105, 1.0, v105
	v_add_f32_e32 v106, 1.0, v106
	v_add_f32_e32 v107, 1.0, v107
	v_rcp_f32_e32 v104, v104
	v_rcp_f32_e32 v105, v105
	v_rcp_f32_e32 v106, v106
	v_rcp_f32_e32 v107, v107
	v_mul_f32_e32 v88, v88, v104
	v_mul_f32_e32 v89, v89, v105
	v_mul_f32_e32 v90, v90, v106
	v_mul_f32_e32 v91, v91, v107
	v_mul_f32_e32 v88, v92, v88
	v_mul_f32_e32 v89, v93, v89
	v_mul_f32_e32 v90, v94, v90
	v_mul_f32_e32 v91, v95, v91
	v_cvt_pk_bf16_f32 v88, v88, v89
	v_cvt_pk_bf16_f32 v89, v90, v91
	global_store_dwordx2 v120, v[88:89], s[94:95]
	s_or_b64 exec, exec, s[4:5]
	s_waitcnt vmcnt(0)
	s_barrier
	s_and_saveexec_b64 s[0:1], s[72:73]
	s_cbranch_execz .LBB0_1069
	s_add_i32 s4, 0, 0x20020
	v_mov_b32_e32 v0, s4
	s_waitcnt vmcnt(0) expcnt(0) lgkmcnt(0)
	ds_read_b32 v2, v0
	s_add_i32 s4, 0, 0x20024
	v_mov_b32_e32 v0, s4
	ds_read_b32 v0, v0
	s_waitcnt lgkmcnt(1)
	v_cmp_ne_u32_e32 vcc, 0, v2
	s_cbranch_vccnz .LBB0_1033
	v_readlane_b32 s4, v248, 2
	v_readlane_b32 s5, v248, 3
	v_readlane_b32 s6, v248, 1
	s_mul_i32 s29, s5, s6
	s_mul_i32 s29, s29, s4
	s_add_u32 s4, s94, 0x40200
	s_addc_u32 s5, s95, 0
	s_add_u32 s6, s94, 0x40400
	s_addc_u32 s7, s95, 0
	s_add_u32 s8, s94, 0x40500
	s_addc_u32 s9, s95, 0
	s_add_u32 s16, s94, 0x40600
	s_addc_u32 s17, s95, 0
	s_add_u32 s18, s94, 0x40700
	s_addc_u32 s19, s95, 0
	s_add_u32 s20, s94, 0x40800
	s_addc_u32 s21, s95, 0
	s_add_u32 s22, s94, 0x40900
	s_addc_u32 s23, s95, 0
	s_add_u32 s24, s94, 0x40a00
	s_addc_u32 s25, s95, 0
	s_add_u32 s34, s94, 0x40b00
	s_addc_u32 s35, s95, 0
	s_add_u32 s38, s94, 0x40c00
	s_addc_u32 s39, s95, 0
	s_add_u32 s40, s94, 0x40d00
	s_addc_u32 s41, s95, 0
	s_add_u32 s42, s94, 0x40e00
	s_addc_u32 s43, s95, 0
	s_add_u32 s44, s94, 0x40f00
	s_addc_u32 s45, s95, 0
	s_add_u32 s46, s94, 0x41000
	s_addc_u32 s47, s95, 0
	s_add_u32 s48, s94, 0x41100
	s_addc_u32 s49, s95, 0
	s_add_u32 s50, s94, 0x41200
	s_addc_u32 s51, s95, 0
	s_add_u32 s52, s94, 0x41300
	s_addc_u32 s53, s95, 0
	s_mov_b32 s30, 1
	v_mov_b32_e32 v16, 0
	s_branch .LBB0_1021
